# CMP2 (compression MLP layer 2) moved from f32 VALU dot products to exact-f32 matrix cores (v_mfma_f32_16x16x4_f32), 16 rows per wave, H rows prefetched before the weight fill
# speedup vs baseline: 1.0062x; 1.0055x over previous
.LBB0_1188:
	s_cmp_lt_i32 s46, 10
	s_cselect_b64 s[2:3], -1, 0
	s_and_b64 s[2:3], s[2:3], s[0:1]
	s_andn2_b64 vcc, exec, s[2:3]
	s_cbranch_vccnz .LBB0_1205
	v_lshrrev_b32_e32 v200, 6, v188
	v_and_b32_e32 v201, 15, v188
	v_bfe_u32 v202, v188, 4, 2
	v_lshl_add_u32 v203, v200, 4, v201
	s_lshl_b32 s0, s33, 7
	v_add_u32_e32 v203, s0, v203
	v_lshlrev_b32_e32 v204, 9, v203
	v_lshl_add_u32 v204, v202, 7, v204
	s_add_u32 s0, s44, 0x36040000
	s_addc_u32 s1, s45, 0
	global_load_dwordx4 v[100:103], v204, s[0:1]
	global_load_dwordx4 v[104:107], v204, s[0:1] offset:16
	global_load_dwordx4 v[108:111], v204, s[0:1] offset:32
	global_load_dwordx4 v[112:115], v204, s[0:1] offset:48
	global_load_dwordx4 v[116:119], v204, s[0:1] offset:64
	global_load_dwordx4 v[120:123], v204, s[0:1] offset:80
	global_load_dwordx4 v[124:127], v204, s[0:1] offset:96
	global_load_dwordx4 v[128:131], v204, s[0:1] offset:112
	v_lshrrev_b32_e32 v5, 9, v188
	v_sub_u32_e32 v0, 30, v5
	v_lshrrev_b32_e32 v0, 1, v0
	v_readlane_b32 s4, v235, 33
	v_add_u32_e32 v7, 1, v0
	v_add_u32_e32 v189, 0x200, v188
	v_lshlrev_b32_e32 v4, 2, v188
	v_readlane_b32 s12, v235, 41
	v_readlane_b32 s13, v235, 42
	v_readlane_b32 s16, v235, 45
	v_readlane_b32 s17, v235, 46
	v_and_b32_e32 v8, 24, v7
	v_add_u32_e32 v6, 0, v4
	s_mov_b64 s[0:1], 0
	v_mov_b32_e32 v3, 0
	s_waitcnt lgkmcnt(0)
	v_mov_b64_e32 v[0:1], v[188:189]
	s_mov_b64 s[12:13], s[16:17]
	v_readlane_b32 s5, v235, 34
	v_readlane_b32 s6, v235, 35
	v_readlane_b32 s7, v235, 36
	v_readlane_b32 s8, v235, 37
	v_readlane_b32 s9, v235, 38
	v_readlane_b32 s10, v235, 39
	v_readlane_b32 s11, v235, 40
	v_readlane_b32 s14, v235, 43
	v_readlane_b32 s15, v235, 44
	v_readlane_b32 s18, v235, 47
	v_readlane_b32 s19, v235, 48

.LBB0_1197:
	s_or_b64 exec, exec, s[0:1]
	s_waitcnt lgkmcnt(0)
	s_barrier
	s_mov_b64 s[4:5], exec
	s_lshr_b32 s0, s33, 7
	s_lshl_b32 s0, s0, 15
	v_lshlrev_b32_e32 v206, 13, v202
	v_lshl_add_u32 v206, v201, 2, v206
	v_add_u32_e32 v206, s0, v206
	v_mov_b64_e32 v[132:133], 0
	v_mov_b64_e32 v[134:135], 0
	v_mov_b64_e32 v[136:137], 0
	v_mov_b64_e32 v[138:139], 0
	v_mov_b64_e32 v[140:141], 0
	v_mov_b64_e32 v[142:143], 0
	v_mov_b64_e32 v[144:145], 0
	v_mov_b64_e32 v[146:147], 0
	ds_read_b32 v148, v206 offset:0
	ds_read_b32 v149, v206 offset:64
	ds_read_b32 v150, v206 offset:128
	ds_read_b32 v151, v206 offset:192
	ds_read_b32 v152, v206 offset:256
	ds_read_b32 v153, v206 offset:320
	ds_read_b32 v154, v206 offset:384
	ds_read_b32 v155, v206 offset:448
	ds_read_b32 v156, v206 offset:512
	ds_read_b32 v157, v206 offset:576
	ds_read_b32 v158, v206 offset:640
	ds_read_b32 v159, v206 offset:704
	s_waitcnt vmcnt(0)
	ds_read_b32 v160, v206 offset:768
	ds_read_b32 v161, v206 offset:832
	ds_read_b32 v162, v206 offset:896
	ds_read_b32 v163, v206 offset:960
	s_waitcnt lgkmcnt(12)
	v_mfma_f32_16x16x4_f32 v[132:135], v100, v148, v[132:135]
	v_mfma_f32_16x16x4_f32 v[136:139], v100, v149, v[136:139]
	v_mfma_f32_16x16x4_f32 v[140:143], v100, v150, v[140:143]
	v_mfma_f32_16x16x4_f32 v[144:147], v100, v151, v[144:147]
	ds_read_b32 v148, v206 offset:1024
	ds_read_b32 v149, v206 offset:1088
	ds_read_b32 v150, v206 offset:1152
	ds_read_b32 v151, v206 offset:1216
	s_waitcnt lgkmcnt(12)
	v_mfma_f32_16x16x4_f32 v[132:135], v101, v152, v[132:135]
	v_mfma_f32_16x16x4_f32 v[136:139], v101, v153, v[136:139]
	v_mfma_f32_16x16x4_f32 v[140:143], v101, v154, v[140:143]
	v_mfma_f32_16x16x4_f32 v[144:147], v101, v155, v[144:147]
	ds_read_b32 v152, v206 offset:1280
	ds_read_b32 v153, v206 offset:1344
	ds_read_b32 v154, v206 offset:1408
	ds_read_b32 v155, v206 offset:1472
	s_waitcnt lgkmcnt(12)
	v_mfma_f32_16x16x4_f32 v[132:135], v102, v156, v[132:135]
	v_mfma_f32_16x16x4_f32 v[136:139], v102, v157, v[136:139]
	v_mfma_f32_16x16x4_f32 v[140:143], v102, v158, v[140:143]
	v_mfma_f32_16x16x4_f32 v[144:147], v102, v159, v[144:147]
	ds_read_b32 v156, v206 offset:1536
	ds_read_b32 v157, v206 offset:1600
	ds_read_b32 v158, v206 offset:1664
	ds_read_b32 v159, v206 offset:1728
	s_waitcnt lgkmcnt(12)
	v_mfma_f32_16x16x4_f32 v[132:135], v103, v160, v[132:135]
	v_mfma_f32_16x16x4_f32 v[136:139], v103, v161, v[136:139]
	v_mfma_f32_16x16x4_f32 v[140:143], v103, v162, v[140:143]
	v_mfma_f32_16x16x4_f32 v[144:147], v103, v163, v[144:147]
	ds_read_b32 v160, v206 offset:1792
	ds_read_b32 v161, v206 offset:1856
	ds_read_b32 v162, v206 offset:1920
	ds_read_b32 v163, v206 offset:1984
	s_waitcnt lgkmcnt(12)
	v_mfma_f32_16x16x4_f32 v[132:135], v104, v148, v[132:135]
	v_mfma_f32_16x16x4_f32 v[136:139], v104, v149, v[136:139]
	v_mfma_f32_16x16x4_f32 v[140:143], v104, v150, v[140:143]
	v_mfma_f32_16x16x4_f32 v[144:147], v104, v151, v[144:147]
	ds_read_b32 v148, v206 offset:2048
	ds_read_b32 v149, v206 offset:2112
	ds_read_b32 v150, v206 offset:2176
	ds_read_b32 v151, v206 offset:2240
	s_waitcnt lgkmcnt(12)
	v_mfma_f32_16x16x4_f32 v[132:135], v105, v152, v[132:135]
	v_mfma_f32_16x16x4_f32 v[136:139], v105, v153, v[136:139]
	v_mfma_f32_16x16x4_f32 v[140:143], v105, v154, v[140:143]
	v_mfma_f32_16x16x4_f32 v[144:147], v105, v155, v[144:147]
	ds_read_b32 v152, v206 offset:2304
	ds_read_b32 v153, v206 offset:2368
	ds_read_b32 v154, v206 offset:2432
	ds_read_b32 v155, v206 offset:2496
	s_waitcnt lgkmcnt(12)
	v_mfma_f32_16x16x4_f32 v[132:135], v106, v156, v[132:135]
	v_mfma_f32_16x16x4_f32 v[136:139], v106, v157, v[136:139]
	v_mfma_f32_16x16x4_f32 v[140:143], v106, v158, v[140:143]
	v_mfma_f32_16x16x4_f32 v[144:147], v106, v159, v[144:147]
	ds_read_b32 v156, v206 offset:2560
	ds_read_b32 v157, v206 offset:2624
	ds_read_b32 v158, v206 offset:2688
	ds_read_b32 v159, v206 offset:2752
	s_waitcnt lgkmcnt(12)
	v_mfma_f32_16x16x4_f32 v[132:135], v107, v160, v[132:135]
	v_mfma_f32_16x16x4_f32 v[136:139], v107, v161, v[136:139]
	v_mfma_f32_16x16x4_f32 v[140:143], v107, v162, v[140:143]
	v_mfma_f32_16x16x4_f32 v[144:147], v107, v163, v[144:147]
	ds_read_b32 v160, v206 offset:2816
	ds_read_b32 v161, v206 offset:2880
	ds_read_b32 v162, v206 offset:2944
	ds_read_b32 v163, v206 offset:3008
	s_waitcnt lgkmcnt(12)
	v_mfma_f32_16x16x4_f32 v[132:135], v108, v148, v[132:135]
	v_mfma_f32_16x16x4_f32 v[136:139], v108, v149, v[136:139]
	v_mfma_f32_16x16x4_f32 v[140:143], v108, v150, v[140:143]
	v_mfma_f32_16x16x4_f32 v[144:147], v108, v151, v[144:147]
	ds_read_b32 v148, v206 offset:3072
	ds_read_b32 v149, v206 offset:3136
	ds_read_b32 v150, v206 offset:3200
	ds_read_b32 v151, v206 offset:3264
	s_waitcnt lgkmcnt(12)
	v_mfma_f32_16x16x4_f32 v[132:135], v109, v152, v[132:135]
	v_mfma_f32_16x16x4_f32 v[136:139], v109, v153, v[136:139]
	v_mfma_f32_16x16x4_f32 v[140:143], v109, v154, v[140:143]
	v_mfma_f32_16x16x4_f32 v[144:147], v109, v155, v[144:147]
	ds_read_b32 v152, v206 offset:3328
	ds_read_b32 v153, v206 offset:3392
	ds_read_b32 v154, v206 offset:3456
	ds_read_b32 v155, v206 offset:3520
	s_waitcnt lgkmcnt(12)
	v_mfma_f32_16x16x4_f32 v[132:135], v110, v156, v[132:135]
	v_mfma_f32_16x16x4_f32 v[136:139], v110, v157, v[136:139]
	v_mfma_f32_16x16x4_f32 v[140:143], v110, v158, v[140:143]
	v_mfma_f32_16x16x4_f32 v[144:147], v110, v159, v[144:147]
	ds_read_b32 v156, v206 offset:3584
	ds_read_b32 v157, v206 offset:3648
	ds_read_b32 v158, v206 offset:3712
	ds_read_b32 v159, v206 offset:3776
	s_waitcnt lgkmcnt(12)
	v_mfma_f32_16x16x4_f32 v[132:135], v111, v160, v[132:135]
	v_mfma_f32_16x16x4_f32 v[136:139], v111, v161, v[136:139]
	v_mfma_f32_16x16x4_f32 v[140:143], v111, v162, v[140:143]
	v_mfma_f32_16x16x4_f32 v[144:147], v111, v163, v[144:147]
	ds_read_b32 v160, v206 offset:3840
	ds_read_b32 v161, v206 offset:3904
	ds_read_b32 v162, v206 offset:3968
	ds_read_b32 v163, v206 offset:4032
	s_waitcnt lgkmcnt(12)
	v_mfma_f32_16x16x4_f32 v[132:135], v112, v148, v[132:135]
	v_mfma_f32_16x16x4_f32 v[136:139], v112, v149, v[136:139]
	v_mfma_f32_16x16x4_f32 v[140:143], v112, v150, v[140:143]
	v_mfma_f32_16x16x4_f32 v[144:147], v112, v151, v[144:147]
	ds_read_b32 v148, v206 offset:4096
	ds_read_b32 v149, v206 offset:4160
	ds_read_b32 v150, v206 offset:4224
	ds_read_b32 v151, v206 offset:4288
	s_waitcnt lgkmcnt(12)
	v_mfma_f32_16x16x4_f32 v[132:135], v113, v152, v[132:135]
	v_mfma_f32_16x16x4_f32 v[136:139], v113, v153, v[136:139]
	v_mfma_f32_16x16x4_f32 v[140:143], v113, v154, v[140:143]
	v_mfma_f32_16x16x4_f32 v[144:147], v113, v155, v[144:147]
	ds_read_b32 v152, v206 offset:4352
	ds_read_b32 v153, v206 offset:4416
	ds_read_b32 v154, v206 offset:4480
	ds_read_b32 v155, v206 offset:4544
	s_waitcnt lgkmcnt(12)
	v_mfma_f32_16x16x4_f32 v[132:135], v114, v156, v[132:135]
	v_mfma_f32_16x16x4_f32 v[136:139], v114, v157, v[136:139]
	v_mfma_f32_16x16x4_f32 v[140:143], v114, v158, v[140:143]
	v_mfma_f32_16x16x4_f32 v[144:147], v114, v159, v[144:147]
	ds_read_b32 v156, v206 offset:4608
	ds_read_b32 v157, v206 offset:4672
	ds_read_b32 v158, v206 offset:4736
	ds_read_b32 v159, v206 offset:4800
	s_waitcnt lgkmcnt(12)
	v_mfma_f32_16x16x4_f32 v[132:135], v115, v160, v[132:135]
	v_mfma_f32_16x16x4_f32 v[136:139], v115, v161, v[136:139]
	v_mfma_f32_16x16x4_f32 v[140:143], v115, v162, v[140:143]
	v_mfma_f32_16x16x4_f32 v[144:147], v115, v163, v[144:147]
	ds_read_b32 v160, v206 offset:4864
	ds_read_b32 v161, v206 offset:4928
	ds_read_b32 v162, v206 offset:4992
	ds_read_b32 v163, v206 offset:5056
	s_waitcnt lgkmcnt(12)
	v_mfma_f32_16x16x4_f32 v[132:135], v116, v148, v[132:135]
	v_mfma_f32_16x16x4_f32 v[136:139], v116, v149, v[136:139]
	v_mfma_f32_16x16x4_f32 v[140:143], v116, v150, v[140:143]
	v_mfma_f32_16x16x4_f32 v[144:147], v116, v151, v[144:147]
	ds_read_b32 v148, v206 offset:5120
	ds_read_b32 v149, v206 offset:5184
	ds_read_b32 v150, v206 offset:5248
	ds_read_b32 v151, v206 offset:5312
	s_waitcnt lgkmcnt(12)
	v_mfma_f32_16x16x4_f32 v[132:135], v117, v152, v[132:135]
	v_mfma_f32_16x16x4_f32 v[136:139], v117, v153, v[136:139]
	v_mfma_f32_16x16x4_f32 v[140:143], v117, v154, v[140:143]
	v_mfma_f32_16x16x4_f32 v[144:147], v117, v155, v[144:147]
	ds_read_b32 v152, v206 offset:5376
	ds_read_b32 v153, v206 offset:5440
	ds_read_b32 v154, v206 offset:5504
	ds_read_b32 v155, v206 offset:5568
	s_waitcnt lgkmcnt(12)
	v_mfma_f32_16x16x4_f32 v[132:135], v118, v156, v[132:135]
	v_mfma_f32_16x16x4_f32 v[136:139], v118, v157, v[136:139]
	v_mfma_f32_16x16x4_f32 v[140:143], v118, v158, v[140:143]
	v_mfma_f32_16x16x4_f32 v[144:147], v118, v159, v[144:147]
	ds_read_b32 v156, v206 offset:5632
	ds_read_b32 v157, v206 offset:5696
	ds_read_b32 v158, v206 offset:5760
	ds_read_b32 v159, v206 offset:5824
	s_waitcnt lgkmcnt(12)
	v_mfma_f32_16x16x4_f32 v[132:135], v119, v160, v[132:135]
	v_mfma_f32_16x16x4_f32 v[136:139], v119, v161, v[136:139]
	v_mfma_f32_16x16x4_f32 v[140:143], v119, v162, v[140:143]
	v_mfma_f32_16x16x4_f32 v[144:147], v119, v163, v[144:147]
	ds_read_b32 v160, v206 offset:5888
	ds_read_b32 v161, v206 offset:5952
	ds_read_b32 v162, v206 offset:6016
	ds_read_b32 v163, v206 offset:6080
	s_waitcnt lgkmcnt(12)
	v_mfma_f32_16x16x4_f32 v[132:135], v120, v148, v[132:135]
	v_mfma_f32_16x16x4_f32 v[136:139], v120, v149, v[136:139]
	v_mfma_f32_16x16x4_f32 v[140:143], v120, v150, v[140:143]
	v_mfma_f32_16x16x4_f32 v[144:147], v120, v151, v[144:147]
	ds_read_b32 v148, v206 offset:6144
	ds_read_b32 v149, v206 offset:6208
	ds_read_b32 v150, v206 offset:6272
	ds_read_b32 v151, v206 offset:6336
	s_waitcnt lgkmcnt(12)
	v_mfma_f32_16x16x4_f32 v[132:135], v121, v152, v[132:135]
	v_mfma_f32_16x16x4_f32 v[136:139], v121, v153, v[136:139]
	v_mfma_f32_16x16x4_f32 v[140:143], v121, v154, v[140:143]
	v_mfma_f32_16x16x4_f32 v[144:147], v121, v155, v[144:147]
	ds_read_b32 v152, v206 offset:6400
	ds_read_b32 v153, v206 offset:6464
	ds_read_b32 v154, v206 offset:6528
	ds_read_b32 v155, v206 offset:6592
	s_waitcnt lgkmcnt(12)
	v_mfma_f32_16x16x4_f32 v[132:135], v122, v156, v[132:135]
	v_mfma_f32_16x16x4_f32 v[136:139], v122, v157, v[136:139]
	v_mfma_f32_16x16x4_f32 v[140:143], v122, v158, v[140:143]
	v_mfma_f32_16x16x4_f32 v[144:147], v122, v159, v[144:147]
	ds_read_b32 v156, v206 offset:6656
	ds_read_b32 v157, v206 offset:6720
	ds_read_b32 v158, v206 offset:6784
	ds_read_b32 v159, v206 offset:6848
	s_waitcnt lgkmcnt(12)
	v_mfma_f32_16x16x4_f32 v[132:135], v123, v160, v[132:135]
	v_mfma_f32_16x16x4_f32 v[136:139], v123, v161, v[136:139]
	v_mfma_f32_16x16x4_f32 v[140:143], v123, v162, v[140:143]
	v_mfma_f32_16x16x4_f32 v[144:147], v123, v163, v[144:147]
	ds_read_b32 v160, v206 offset:6912
	ds_read_b32 v161, v206 offset:6976
	ds_read_b32 v162, v206 offset:7040
	ds_read_b32 v163, v206 offset:7104
	s_waitcnt lgkmcnt(12)
	v_mfma_f32_16x16x4_f32 v[132:135], v124, v148, v[132:135]
	v_mfma_f32_16x16x4_f32 v[136:139], v124, v149, v[136:139]
	v_mfma_f32_16x16x4_f32 v[140:143], v124, v150, v[140:143]
	v_mfma_f32_16x16x4_f32 v[144:147], v124, v151, v[144:147]
	ds_read_b32 v148, v206 offset:7168
	ds_read_b32 v149, v206 offset:7232
	ds_read_b32 v150, v206 offset:7296
	ds_read_b32 v151, v206 offset:7360
	s_waitcnt lgkmcnt(12)
	v_mfma_f32_16x16x4_f32 v[132:135], v125, v152, v[132:135]
	v_mfma_f32_16x16x4_f32 v[136:139], v125, v153, v[136:139]
	v_mfma_f32_16x16x4_f32 v[140:143], v125, v154, v[140:143]
	v_mfma_f32_16x16x4_f32 v[144:147], v125, v155, v[144:147]
	ds_read_b32 v152, v206 offset:7424
	ds_read_b32 v153, v206 offset:7488
	ds_read_b32 v154, v206 offset:7552
	ds_read_b32 v155, v206 offset:7616
	s_waitcnt lgkmcnt(12)
	v_mfma_f32_16x16x4_f32 v[132:135], v126, v156, v[132:135]
	v_mfma_f32_16x16x4_f32 v[136:139], v126, v157, v[136:139]
	v_mfma_f32_16x16x4_f32 v[140:143], v126, v158, v[140:143]
	v_mfma_f32_16x16x4_f32 v[144:147], v126, v159, v[144:147]
	ds_read_b32 v156, v206 offset:7680
	ds_read_b32 v157, v206 offset:7744
	ds_read_b32 v158, v206 offset:7808
	ds_read_b32 v159, v206 offset:7872
	s_waitcnt lgkmcnt(12)
	v_mfma_f32_16x16x4_f32 v[132:135], v127, v160, v[132:135]
	v_mfma_f32_16x16x4_f32 v[136:139], v127, v161, v[136:139]
	v_mfma_f32_16x16x4_f32 v[140:143], v127, v162, v[140:143]
	v_mfma_f32_16x16x4_f32 v[144:147], v127, v163, v[144:147]
	ds_read_b32 v160, v206 offset:7936
	ds_read_b32 v161, v206 offset:8000
	ds_read_b32 v162, v206 offset:8064
	ds_read_b32 v163, v206 offset:8128
	s_waitcnt lgkmcnt(12)
	v_mfma_f32_16x16x4_f32 v[132:135], v128, v148, v[132:135]
	v_mfma_f32_16x16x4_f32 v[136:139], v128, v149, v[136:139]
	v_mfma_f32_16x16x4_f32 v[140:143], v128, v150, v[140:143]
	v_mfma_f32_16x16x4_f32 v[144:147], v128, v151, v[144:147]
	s_waitcnt lgkmcnt(8)
	v_mfma_f32_16x16x4_f32 v[132:135], v129, v152, v[132:135]
	v_mfma_f32_16x16x4_f32 v[136:139], v129, v153, v[136:139]
	v_mfma_f32_16x16x4_f32 v[140:143], v129, v154, v[140:143]
	v_mfma_f32_16x16x4_f32 v[144:147], v129, v155, v[144:147]
	s_waitcnt lgkmcnt(4)
	v_mfma_f32_16x16x4_f32 v[132:135], v130, v156, v[132:135]
	v_mfma_f32_16x16x4_f32 v[136:139], v130, v157, v[136:139]
	v_mfma_f32_16x16x4_f32 v[140:143], v130, v158, v[140:143]
	v_mfma_f32_16x16x4_f32 v[144:147], v130, v159, v[144:147]
	s_waitcnt lgkmcnt(0)
	v_mfma_f32_16x16x4_f32 v[132:135], v131, v160, v[132:135]
	v_mfma_f32_16x16x4_f32 v[136:139], v131, v161, v[136:139]
	v_mfma_f32_16x16x4_f32 v[140:143], v131, v162, v[140:143]
	v_mfma_f32_16x16x4_f32 v[144:147], v131, v163, v[144:147]
	s_nop 7
	s_nop 7
	s_nop 3
	s_movk_i32 s12, 0x7fff
	v_lshlrev_b32_e32 v207, 2, v202
	v_lshl_add_u32 v207, v200, 4, v207
	s_lshl_b32 s0, s33, 7
	v_add_u32_e32 v207, s0, v207
	v_and_b32_e32 v208, 0x1fc, v207
	s_movk_i32 s14, 0x1fc
	v_cmp_ne_u32_e32 vcc, s14, v208
	v_lshlrev_b32_e32 v207, 7, v207
	v_lshl_add_u32 v207, v201, 1, v207
	s_add_u32 s0, s44, 0x35c40000
	s_addc_u32 s1, s45, 0
	v_bfe_u32 v209, v132, 16, 1
	v_add3_u32 v132, v132, v209, s12
	v_lshrrev_b32_e32 v132, 16, v132
	v_cndmask_b32_e32 v132, 0, v132, vcc
	global_store_short v207, v132, s[0:1]
	v_bfe_u32 v209, v133, 16, 1
	v_add3_u32 v133, v133, v209, s12
	v_lshrrev_b32_e32 v133, 16, v133
	v_cndmask_b32_e32 v133, 0, v133, vcc
	global_store_short v207, v133, s[0:1] offset:128
	v_bfe_u32 v209, v134, 16, 1
	v_add3_u32 v134, v134, v209, s12
	v_lshrrev_b32_e32 v134, 16, v134
	v_cndmask_b32_e32 v134, 0, v134, vcc
	global_store_short v207, v134, s[0:1] offset:256
	v_bfe_u32 v209, v135, 16, 1
	v_add3_u32 v135, v135, v209, s12
	v_lshrrev_b32_e32 v135, 16, v135
	v_cndmask_b32_e32 v135, 0, v135, vcc
	global_store_short v207, v135, s[0:1] offset:384
	v_bfe_u32 v209, v136, 16, 1
	v_add3_u32 v136, v136, v209, s12
	v_lshrrev_b32_e32 v136, 16, v136
	v_cndmask_b32_e32 v136, 0, v136, vcc
	global_store_short v207, v136, s[0:1] offset:32
	v_bfe_u32 v209, v137, 16, 1
	v_add3_u32 v137, v137, v209, s12
	v_lshrrev_b32_e32 v137, 16, v137
	v_cndmask_b32_e32 v137, 0, v137, vcc
	global_store_short v207, v137, s[0:1] offset:160
	v_bfe_u32 v209, v138, 16, 1
	v_add3_u32 v138, v138, v209, s12
	v_lshrrev_b32_e32 v138, 16, v138
	v_cndmask_b32_e32 v138, 0, v138, vcc
	global_store_short v207, v138, s[0:1] offset:288
	v_bfe_u32 v209, v139, 16, 1
	v_add3_u32 v139, v139, v209, s12
	v_lshrrev_b32_e32 v139, 16, v139
	v_cndmask_b32_e32 v139, 0, v139, vcc
	global_store_short v207, v139, s[0:1] offset:416
	v_bfe_u32 v209, v140, 16, 1
	v_add3_u32 v140, v140, v209, s12
	v_lshrrev_b32_e32 v140, 16, v140
	v_cndmask_b32_e32 v140, 0, v140, vcc
	global_store_short v207, v140, s[0:1] offset:64
	v_bfe_u32 v209, v141, 16, 1
	v_add3_u32 v141, v141, v209, s12
	v_lshrrev_b32_e32 v141, 16, v141
	v_cndmask_b32_e32 v141, 0, v141, vcc
	global_store_short v207, v141, s[0:1] offset:192
	v_bfe_u32 v209, v142, 16, 1
	v_add3_u32 v142, v142, v209, s12
	v_lshrrev_b32_e32 v142, 16, v142
	v_cndmask_b32_e32 v142, 0, v142, vcc
	global_store_short v207, v142, s[0:1] offset:320
	v_bfe_u32 v209, v143, 16, 1
	v_add3_u32 v143, v143, v209, s12
	v_lshrrev_b32_e32 v143, 16, v143
	v_cndmask_b32_e32 v143, 0, v143, vcc
	global_store_short v207, v143, s[0:1] offset:448
	v_bfe_u32 v209, v144, 16, 1
	v_add3_u32 v144, v144, v209, s12
	v_lshrrev_b32_e32 v144, 16, v144
	v_cndmask_b32_e32 v144, 0, v144, vcc
	global_store_short v207, v144, s[0:1] offset:96
	v_bfe_u32 v209, v145, 16, 1
	v_add3_u32 v145, v145, v209, s12
	v_lshrrev_b32_e32 v145, 16, v145
	v_cndmask_b32_e32 v145, 0, v145, vcc
	global_store_short v207, v145, s[0:1] offset:224
	v_bfe_u32 v209, v146, 16, 1
	v_add3_u32 v146, v146, v209, s12
	v_lshrrev_b32_e32 v146, 16, v146
	v_cndmask_b32_e32 v146, 0, v146, vcc
	global_store_short v207, v146, s[0:1] offset:352
	v_bfe_u32 v209, v147, 16, 1
	v_add3_u32 v147, v147, v209, s12
	v_lshrrev_b32_e32 v147, 16, v147
	v_cndmask_b32_e32 v147, 0, v147, vcc
	global_store_short v207, v147, s[0:1] offset:480
